# attention main loop: K/V prefetch loads land directly in their registers; rotation waits on loads one iteration old instead of just-issued loads
# speedup vs baseline: 1.0013x; 1.0013x over previous
; #define LAS __attribute__((address_space(3)))
; __device__ __forceinline__ void unit(unsigned char* ws, LAS unsigned char* lds, int b, int h, int mp, int qb, const int tid_in) {
;     int tid = tid_in; asm volatile("" : "+v"(tid));
;     const int lane = tid & 63, w = __builtin_amdgcn_readfirstlane(tid >> 6), fr = lane & 15, fq = lane >> 4;
;     const bf16_t* Q = (const bf16_t*)(ws + WS_R + R_Q) + (size_t)b * SEQ * 512 + (h * 2 + mp) * 64;
;     const bf16_t* K = (const bf16_t*)(ws + WS_R + R_K) + (size_t)b * SEQ * 512 + (h * 2 + mp) * 64;
;     const bf16_t* V = (const bf16_t*)(ws + WS_R + R_V) + (size_t)b * SEQ * 512 + h * 128;
;     bf16_t* O = (bf16_t*)(ws + WS_XB) + (size_t)b * SEQ * 1024 + h * 256 + mp * 128;
;     const float* BTg = (const float*)(ws + WS_BT) + h * 128;
;     constexpr int KVB = (64 + 128) * KP;
;     LAS bf16_t* KV0 = (LAS bf16_t*)lds; LAS float* TB = (LAS float*)(KV0 + 2 * KVB);
;     const int q0 = qb * 256, qw0 = q0 + 32 * w, NT = 4 * qb + 4;
;     __syncthreads();
;     { const int d_ = tid - 256; TB[tid] = d_ < 0 ? -INFINITY : (d_ < 128 ? BTg[d_] : 0.f); }
;     bf16x8 qf[2][2];
; #pragma unroll
;     for (int g = 0; g < 2; ++g) { const bf16_t* qp = Q + (size_t)(qw0 + 16 * g + fr) * 512 + 8 * fq; qf[g][0] = *(const bf16x8*)qp; qf[g][1] = *(const bf16x8*)(qp + 32); }
;     float m[2] = {0.f, 0.f}; f32x4 lacc[2] = {(f32x4){0.f, 0.f, 0.f, 0.f}, (f32x4){0.f, 0.f, 0.f, 0.f}}; f32x4 o[2][8];
;     const bf16x8 onesf = {0x3F80, 0x3F80, 0x3F80, 0x3F80, 0x3F80, 0x3F80, 0x3F80, 0x3F80};
; #pragma unroll
;     for (int g = 0; g < 2; ++g)
; #pragma unroll
;         for (int et = 0; et < 8; ++et) o[g][et] = (f32x4){0.f, 0.f, 0.f, 0.f};
;     const int sr = tid >> 3, sc = tid & 7;
;     const bf16_t* kg = K + (size_t)sr * 512 + sc * 8;
;     const int vp = tid >> 4, vc = tid & 15;
;     const bf16_t* vg = V + (size_t)(2 * vp) * 512 + vc * 8;
;     u32x4 kA = *(const u32x4*)kg, vA0 = *(const u32x4*)vg, vA1 = *(const u32x4*)(vg + 512);
;     u32x4 kB = *(const u32x4*)(kg + (size_t)64 * 512), vB0 = *(const u32x4*)(vg + (size_t)64 * 512), vB1 = *(const u32x4*)(vg + (size_t)64 * 512 + 512);
;     ...
;     FA3_STAGE(0);
;     kA = kB; vA0 = vB0; vA1 = vB1;
;     { const size_t off = (size_t)2 * 64 * 512; kB = *(const u32x4*)(kg + off); vB0 = *(const u32x4*)(vg + off); vB1 = *(const u32x4*)(vg + off + 512); }
;     __syncthreads();
.LBB0_181:
	s_or_b64 exec, exec, s[22:23]
	v_bfe_u32 v37, v2, 4, 2
	v_lshlrev_b32_e32 v0, 4, v37
	v_ashrrev_i32_e32 v18, 3, v2
	v_lshl_add_u64 v[16:17], s[18:19], 0, v[0:1]
	v_ashrrev_i32_e32 v19, 31, v18
	v_lshlrev_b32_e32 v0, 3, v2
	v_lshlrev_b64 v[20:21], 10, v[18:19]
	v_and_b32_e32 v0, 56, v0
	v_lshl_add_u64 v[4:5], s[48:49], 0, v[20:21]
	v_lshlrev_b32_e32 v0, 1, v0
	v_lshl_add_u64 v[22:23], v[4:5], 0, v[0:1]
	v_and_b32_e32 v4, -2, v18
	v_ashrrev_i32_e32 v5, 31, v4
	v_and_b32_e32 v36, 15, v2
	v_lshlrev_b64 v[24:25], 10, v[4:5]
	v_lshl_add_u64 v[4:5], s[50:51], 0, v[24:25]
	v_lshlrev_b32_e32 v26, 4, v36
	v_mov_b32_e32 v27, v1
	v_lshl_add_u64 v[28:29], v[4:5], 0, v[26:27]
	global_load_dwordx4 v[4:7], v[22:23], off
	global_load_dwordx4 v[8:11], v[28:29], off
	global_load_dwordx4 v[12:15], v[28:29], off offset:1024
	s_ashr_i32 s23, s68, 1
	v_add_co_u32_e32 v32, vcc, s78, v22
	s_lshl_b32 s22, s21, 8
	s_andn2_b32 s23, s23, 31
	v_addc_co_u32_e32 v33, vcc, 0, v23, vcc
	s_add_i32 s23, s23, s22
	v_add_co_u32_e32 v22, vcc, s75, v22
	v_or_b32_e32 v158, s23, v36
	s_nop 0
	v_addc_co_u32_e32 v23, vcc, 0, v23, vcc
	v_lshrrev_b32_e32 v30, 5, v2
	v_ashrrev_i32_e32 v159, 31, v158
	v_or_b32_e32 v156, 16, v158
	global_load_dwordx4 v[110:113], v[32:33], off
	v_add_co_u32_e32 v32, vcc, s78, v28
	v_and_b32_e32 v40, 4, v30
	v_lshlrev_b64 v[30:31], 10, v[158:159]
	v_ashrrev_i32_e32 v157, 31, v156
	v_addc_co_u32_e32 v33, vcc, 0, v29, vcc
	v_lshl_add_u64 v[30:31], v[16:17], 0, v[30:31]
	v_lshlrev_b64 v[34:35], 10, v[156:157]
	v_add_co_u32_e32 v28, vcc, s75, v28
	global_load_dwordx4 v[82:85], v[30:31], off
	global_load_dwordx4 v[78:81], v[30:31], off offset:64
	v_addc_co_u32_e32 v29, vcc, 0, v29, vcc
	v_lshl_add_u64 v[16:17], v[16:17], 0, v[34:35]
	global_load_dwordx4 v[102:105], v[32:33], off
	global_load_dwordx4 v[106:109], v[32:33], off offset:1024
	global_load_dwordx4 v[90:93], v[22:23], off
	global_load_dwordx4 v[94:97], v[28:29], off
	global_load_dwordx4 v[98:101], v[28:29], off offset:1024
	global_load_dwordx4 v[86:89], v[16:17], off
	global_load_dwordx4 v[74:77], v[16:17], off offset:64
	v_lshlrev_b32_e32 v19, 2, v2
	v_lshrrev_b32_e32 v27, 2, v2
	v_add_u32_e32 v38, 0, v19
	v_and_b32_e32 v27, 24, v27
	v_and_b32_e32 v41, 2, v18
	s_waitcnt vmcnt(13)
	ds_write_b32 v38, v3 offset:55296
	v_and_or_b32 v3, v18, 32, v27
	s_movk_i32 s26, 0x48
	v_and_b32_e32 v16, 56, v19
	v_or3_b32 v3, v3, v40, v41
	v_mul_lo_u32 v39, v18, s26
	v_add_u32_e32 v3, v3, v16
	v_lshlrev_b32_e32 v171, 1, v39
	v_and_b32_e32 v3, 62, v3
	v_mul_u32_u24_e32 v170, 0x480, v36
	v_add3_u32 v17, 0, v171, v0
	v_lshlrev_b32_e32 v172, 1, v3
	v_add3_u32 v3, 0, v170, v172
	v_add_u32_e32 v3, 0x2400, v3
	v_lshlrev_b32_e32 v169, 3, v37
	v_lshlrev_b32_e32 v165, 2, v37
	v_and_b32_e32 v2, 7, v2
	v_or_b32_e32 v24, v24, v26
	v_lshl_or_b32 v20, v2, 4, v20
	v_sub_u32_e32 v2, v158, v165
	s_lshl_b32 s21, s21, 2
	s_sub_i32 s71, s23, 63
	v_mul_u32_u24_e32 v173, 0x90, v36
	v_mad_u32_u24 v174, v36, s80, 0
	v_lshl_add_u64 v[160:161], s[56:57], 0, v[24:25]
	v_lshl_add_u64 v[162:163], s[58:59], 0, v[20:21]
	v_lshl_add_u32 v176, v2, 2, s93
	s_mov_b32 s68, 3
	s_mov_b32 s69, 0
	s_add_i32 s70, s21, 4
	s_or_b32 s76, s23, 31
	s_sub_i32 s79, 0, s21
	v_mov_b32_e32 v175, 0
	s_mov_b32 s81, s71
	v_mov_b32_e32 v177, 0
	s_waitcnt vmcnt(12)
	ds_write_b128 v17, v[4:7]
	s_waitcnt vmcnt(11)
	v_and_b32_e32 v4, 0xffff, v8
	v_lshrrev_b32_e32 v5, 16, v8
	s_waitcnt vmcnt(10)
	v_lshl_or_b32 v4, v12, 16, v4
	v_and_or_b32 v5, v12, s33, v5
	ds_write2_b32 v3, v4, v5 offset1:36
	v_and_b32_e32 v4, 0xffff, v9
	v_lshrrev_b32_e32 v5, 16, v9
	v_lshl_or_b32 v4, v13, 16, v4
	v_and_or_b32 v5, v13, s33, v5
	ds_write2_b32 v3, v4, v5 offset0:72 offset1:108
	v_and_b32_e32 v4, 0xffff, v10
	v_lshrrev_b32_e32 v5, 16, v10
	v_lshl_or_b32 v4, v14, 16, v4
	v_and_or_b32 v5, v14, s33, v5
	ds_write2_b32 v3, v4, v5 offset0:144 offset1:180
	v_and_b32_e32 v4, 0xffff, v11
	v_lshrrev_b32_e32 v5, 16, v11
	v_lshl_or_b32 v4, v15, 16, v4
	v_and_or_b32 v5, v15, s33, v5
	ds_write2_b32 v3, v4, v5 offset0:216 offset1:252
	v_add_u32_e32 v3, 40, v169
	v_and_b32_e32 v168, 56, v3
	v_add_u32_e32 v3, 48, v169
	v_and_b32_e32 v167, 56, v3
	v_add_u32_e32 v3, 56, v169
	v_mov_b32_e32 v10, v1
	v_mov_b32_e32 v11, v1
	v_mov_b32_e32 v12, v1
	v_mov_b32_e32 v13, v1
	v_and_b32_e32 v166, 56, v3
	v_mov_b64_e32 v[24:25], v[12:13]
	v_mov_b64_e32 v[28:29], v[12:13]
	v_mov_b64_e32 v[32:33], v[12:13]
	v_mov_b64_e32 v[36:37], v[12:13]
	v_mov_b64_e32 v[44:45], v[12:13]
	v_mov_b64_e32 v[48:49], v[12:13]
	v_mov_b64_e32 v[52:53], v[12:13]
	v_mov_b64_e32 v[56:57], v[12:13]
	v_mov_b64_e32 v[60:61], v[12:13]
	v_mov_b64_e32 v[64:65], v[12:13]
	v_mov_b64_e32 v[68:69], v[12:13]
	v_mov_b64_e32 v[20:21], v[12:13]
	v_mov_b64_e32 v[16:17], v[12:13]
	v_mov_b64_e32 v[6:7], v[10:11]
	v_mov_b64_e32 v[2:3], v[10:11]
	v_mov_b64_e32 v[72:73], v[12:13]
	v_mov_b64_e32 v[40:41], v[12:13]
	v_mov_b64_e32 v[22:23], v[10:11]
	v_mov_b64_e32 v[26:27], v[10:11]
	v_mov_b64_e32 v[30:31], v[10:11]
	v_mov_b64_e32 v[34:35], v[10:11]
	v_mov_b64_e32 v[42:43], v[10:11]
	v_mov_b64_e32 v[46:47], v[10:11]
	v_mov_b64_e32 v[50:51], v[10:11]
	v_mov_b64_e32 v[54:55], v[10:11]
	v_mov_b64_e32 v[58:59], v[10:11]
	v_mov_b64_e32 v[62:63], v[10:11]
	v_mov_b64_e32 v[66:67], v[10:11]
	v_mov_b64_e32 v[18:19], v[10:11]
	v_mov_b64_e32 v[14:15], v[10:11]
	v_mov_b64_e32 v[8:9], v[12:13]
	v_mov_b64_e32 v[4:5], v[12:13]
	v_mov_b64_e32 v[70:71], v[10:11]
	v_mov_b64_e32 v[38:39], v[10:11]
	s_waitcnt vmcnt(0) lgkmcnt(0)
	s_barrier
	s_cmp_gt_i32 s69, s76
	s_cbranch_scc1 .LBB0_196
	s_branch .LBB0_183
; #define LAS __attribute__((address_space(3)))
; __device__ __forceinline__ void unit(unsigned char* ws, LAS unsigned char* lds, int b, int h, int mp, int qb, const int tid_in) {
;     ...
;     for (int kt = 0; kt < NT; ++kt) {
;         LAS bf16_t* KS = KV0 + (kt & 1) * KVB; LAS bf16_t* VT = KS + 64 * KP;
;         const int k0 = kt * 64;
;         if (k0 <= qw0 + 31) {
;         f32x4 s[2][4];
; #pragma unroll
;         for (int jt = 0; jt < 4; ++jt) { const bf16x8 kf0 = *(const LAS bf16x8*)(KS + (16 * jt + fr) * KP + 8 * fq), kf1 = *(const LAS bf16x8*)(KS + (16 * jt + fr) * KP + 32 + 8 * fq);
; #pragma unroll
;             for (int g = 0; g < 2; ++g) { const float nm = -m[g]; s[g][jt] = __builtin_amdgcn_mfma_f32_16x16x32_bf16(kf0, qf[g][0], (f32x4){nm, nm, nm, nm}, 0, 0, 0); s[g][jt] = __builtin_amdgcn_mfma_f32_16x16x32_bf16(kf1, qf[g][1], s[g][jt], 0, 0, 0); } }
.LBB0_182:
	s_cmp_gt_i32 s69, s76
	s_cbranch_scc1 .LBB0_196
.LBB0_183:
	s_bitcmp1_b32 s68, 0
	s_cselect_b32 s21, 0, 0x6c00
	v_add_u32_e32 v179, s21, v174
	v_lshl_add_u32 v178, v169, 1, v179
	ds_read_b128 v[114:117], v178
	ds_read_b128 v[118:121], v178 offset:64
	v_xor_b32_e32 v134, 0x80000000, v175
	v_mov_b32_e32 v135, v134
	v_mov_b32_e32 v136, v134
	v_mov_b32_e32 v137, v134
	v_xor_b32_e32 v180, 0x80000000, v177
	v_mov_b32_e32 v181, v180
	v_mov_b32_e32 v182, v180
	s_waitcnt lgkmcnt(1)
	v_mfma_f32_16x16x32_bf16 v[122:125], v[114:117], v[82:85], v[134:137]
	v_mov_b32_e32 v183, v180
	ds_read_b128 v[142:145], v178 offset:4608
	ds_read_b128 v[198:201], v178 offset:6912
	ds_read_b128 v[202:205], v178 offset:6976
	s_nop 0
	v_mfma_f32_16x16x32_bf16 v[114:117], v[114:117], v[86:89], v[180:183]
	s_cmpk_gt_i32 s81, 0x70
	s_cselect_b64 s[22:23], -1, 0
	s_cmpk_lt_i32 s81, 0x71
	s_waitcnt lgkmcnt(3)
	v_mfma_f32_16x16x32_bf16 v[126:129], v[118:121], v[78:81], v[122:125]
	s_mov_b64 s[60:61], -1
	s_nop 1
	ds_read_b128 v[122:125], v178 offset:2304
	s_nop 0
	v_mfma_f32_16x16x32_bf16 v[114:117], v[118:121], v[74:77], v[114:117]
	ds_read_b128 v[118:121], v178 offset:2368
	s_waitcnt lgkmcnt(1)
	v_mfma_f32_16x16x32_bf16 v[130:133], v[122:125], v[82:85], v[134:137]
	v_mfma_f32_16x16x32_bf16 v[122:125], v[122:125], v[86:89], v[180:183]
	s_waitcnt lgkmcnt(0)
	v_mfma_f32_16x16x32_bf16 v[130:133], v[118:121], v[78:81], v[130:133]
	v_mfma_f32_16x16x32_bf16 v[118:121], v[118:121], v[74:77], v[122:125]
	s_nop 4
	ds_read_b128 v[122:125], v178 offset:4672
	v_mfma_f32_16x16x32_bf16 v[138:141], v[142:145], v[82:85], v[134:137]
	v_mfma_f32_16x16x32_bf16 v[142:145], v[142:145], v[86:89], v[180:183]
	v_mfma_f32_16x16x32_bf16 v[134:137], v[198:201], v[82:85], v[134:137]
	s_waitcnt lgkmcnt(0)
	v_mfma_f32_16x16x32_bf16 v[138:141], v[122:125], v[78:81], v[138:141]
	v_mfma_f32_16x16x32_bf16 v[122:125], v[122:125], v[74:77], v[142:145]
	v_mfma_f32_16x16x32_bf16 v[142:145], v[202:205], v[78:81], v[134:137]
	v_mfma_f32_16x16x32_bf16 v[134:137], v[198:201], v[86:89], v[180:183]
	v_mfma_f32_16x16x32_bf16 v[134:137], v[202:205], v[74:77], v[134:137]
	s_cbranch_scc1 .LBB0_185
	s_mov_b64 s[60:61], 0

; __device__ __forceinline__ void unit(unsigned char* ws, LAS unsigned char* lds, int b, int h, int mp, int qb, const int tid_in) {
;     ...
;         if (kt + 1 < NT) { FA3_STAGE((kt + 1) & 1); kA = kB; vA0 = vB0; vA1 = vB1;
;             if (kt + 3 < NT) { const size_t off = (size_t)(kt + 3) * 64 * 512; kB = *(const u32x4*)(kg + off); vB0 = *(const u32x4*)(vg + off); vB1 = *(const u32x4*)(vg + off + 512); } }
.LBB0_196:
	s_bitcmp1_b32 s68, 0
	s_cselect_b32 s21, 0x6c00, 0
	s_add_i32 s22, s21, 0
	v_add3_u32 v114, s22, v171, v0
	s_waitcnt vmcnt(9)
	ds_write_b128 v114, v[110:113]
	s_waitcnt vmcnt(6)
	v_and_b32_e32 v110, 0xffff, v102
	v_add3_u32 v111, s22, v170, v172
	v_lshrrev_b32_e32 v102, 16, v102
	s_waitcnt vmcnt(5)
	v_lshl_or_b32 v110, v106, 16, v110
	v_and_or_b32 v102, v106, s33, v102
	v_add_u32_e32 v106, 0x2400, v111
	ds_write2_b32 v106, v110, v102 offset1:36
	v_and_b32_e32 v102, 0xffff, v103
	v_lshrrev_b32_e32 v103, 16, v103
	v_lshl_or_b32 v102, v107, 16, v102
	v_and_or_b32 v103, v107, s33, v103
	ds_write2_b32 v106, v102, v103 offset0:72 offset1:108
	v_and_b32_e32 v102, 0xffff, v104
	v_lshrrev_b32_e32 v103, 16, v104
	v_lshl_or_b32 v102, v108, 16, v102
	v_and_or_b32 v103, v108, s33, v103
	ds_write2_b32 v106, v102, v103 offset0:144 offset1:180
	v_and_b32_e32 v102, 0xffff, v105
	v_lshrrev_b32_e32 v103, 16, v105
	v_lshl_or_b32 v102, v109, 16, v102
	v_and_or_b32 v103, v109, s33, v103
	ds_write2_b32 v106, v102, v103 offset0:216 offset1:252
	s_waitcnt vmcnt(0)
	v_mov_b64_e32 v[110:111], v[90:91]
	v_mov_b64_e32 v[112:113], v[92:93]
	v_mov_b64_e32 v[102:103], v[94:95]
	v_mov_b64_e32 v[104:105], v[96:97]
	v_mov_b64_e32 v[106:107], v[98:99]
	v_mov_b64_e32 v[108:109], v[100:101]
	s_cmp_ge_u32 s68, s70
	s_cbranch_scc1 .LBB0_198
	v_lshl_add_u64 v[114:115], v[160:161], 0, s[14:15]
	v_add_co_u32_e32 v114, vcc, 0xa630000, v114
	v_lshl_add_u64 v[116:117], v[162:163], 0, s[14:15]
	s_nop 0
	v_addc_co_u32_e32 v115, vcc, 0, v115, vcc
	global_load_dwordx4 v[90:93], v[116:117], off
	global_load_dwordx4 v[94:97], v[114:115], off
	global_load_dwordx4 v[98:101], v[114:115], off offset:1024
